# v1 + ret_out row-norm wave_sum via DPP and permlane swaps instead of six ds_bpermute round trips
# baseline (speedup 1.0000x reference)
; __device__ __forceinline__ float sigm(float x) { return __builtin_amdgcn_rcpf(1.0f + __expf(-x)); }
; __device__ __forceinline__ float bflo(unsigned w) { return __uint_as_float(w << 16); }
; __device__ __forceinline__ float bfhi(unsigned w) { return __uint_as_float(w & 0xffff0000u); }
; #define LAS __attribute__((address_space(3)))
; __device__ __forceinline__ unsigned pk2(float lo, float hi) { return pg8::cvt_pk_bf16(lo, hi); }
; __device__ __forceinline__ void ret_out_unit(LAS unsigned char* lds, const bf16* Z, const bf16* RT, const float* subg, bf16* YB, int h, int n, int tid) {
;     ...
;     for (int rr = 0; rr < 16; ++rr) {
;         const int i = wid * 16 + rr;
;         const f32x2 x = *(const LAS f32x2*)(OF + i * 132 + 2 * lane);
;         const float r = rsqrtf(wave_sum(x.x * x.x + x.y * x.y) * (1.f / 128.f) + EPS);
;         const size_t row = (size_t)(n * 128 + i);
;         const unsigned gw = *(const unsigned*)(Z + row * NIN + ZGR + h * 128 + 2 * lane);
;         const float ga = bflo(gw), gb = bfhi(gw);
;         *(unsigned*)(YB + row * 1024 + h * 128 + 2 * lane) = pk2(x.x * r * g2.x * (ga * sigm(ga)), x.y * r * g2.y * (gb * sigm(gb)));
.LBB0_15:
	v_add_u32_e32 v12, s5, v150
	ds_read2_b64 v[2:5], v12 offset1:66
	v_lshl_add_u64 v[10:11], v[92:93], 0, s[78:79]
	s_mov_b32 s1, 0x11203000
	s_addk_i32 s5, 0x840
	s_cmpk_lg_i32 s5, 0x2100
	s_waitcnt lgkmcnt(0)
	v_pk_mul_f32 v[8:9], v[2:3], v[2:3]
	s_nop 0
	v_add_f32_e32 v0, v8, v9
	s_waitcnt lgkmcnt(0)
	s_nop 1
	v_add_f32_dpp v0, v0, v0 quad_perm:[1,0,3,2] row_mask:0xf bank_mask:0xf
	s_waitcnt lgkmcnt(0)
	s_nop 1
	v_add_f32_dpp v0, v0, v0 quad_perm:[2,3,0,1] row_mask:0xf bank_mask:0xf
	s_waitcnt lgkmcnt(0)
	s_nop 1
	v_add_f32_dpp v0, v0, v0 row_half_mirror row_mask:0xf bank_mask:0xf
	s_waitcnt lgkmcnt(0)
	s_nop 1
	v_add_f32_dpp v0, v0, v0 row_mirror row_mask:0xf bank_mask:0xf
	s_waitcnt lgkmcnt(0)
	v_mov_b32_e32 v8, v0
	s_nop 1
	v_permlane16_swap_b32_e32 v0, v8
	v_add_f32_e32 v0, v0, v8
	s_waitcnt lgkmcnt(0)
	v_mov_b32_e32 v8, v0
	s_nop 1
	v_permlane32_swap_b32_e32 v0, v8
	v_add_f32_e32 v0, v0, v8
	v_fmamk_f32 v0, v0, 0x3c000000, v232
	v_cmp_gt_f32_e64 s[70:71], s4, v0
	v_mul_f32_e32 v8, 0x4b800000, v0
	s_nop 0
	v_cndmask_b32_e64 v0, v0, v8, s[70:71]
	v_rsq_f32_e32 v0, v0
	s_nop 0
	v_mul_f32_e32 v8, 0x45800000, v0
	v_cndmask_b32_e64 v0, v0, v8, s[70:71]
	v_add_co_u32_e64 v8, s[70:71], s1, v10
	v_pk_mul_f32 v[2:3], v[2:3], v[0:1] op_sel_hi:[1,0]
	s_nop 0
	v_addc_co_u32_e64 v9, s[70:71], 0, v11, s[70:71]
	global_load_dword v9, v[8:9], off
	s_waitcnt vmcnt(1)
	v_pk_mul_f32 v[2:3], v[6:7], v[2:3]
	s_mov_b32 s1, 0x2d200000
	s_waitcnt vmcnt(0)
	v_lshlrev_b32_e32 v8, 16, v9
	v_and_b32_e32 v9, 0xffff0000, v9
	v_mul_f32_e32 v13, 0xbfb8aa3b, v8
	v_mul_f32_e32 v0, 0xbfb8aa3b, v9
	v_exp_f32_e32 v13, v13
	v_exp_f32_e32 v0, v0
	v_add_f32_e32 v13, 1.0, v13
	v_add_f32_e32 v0, 1.0, v0
	v_rcp_f32_e32 v14, v13
	v_rcp_f32_e32 v15, v0
	s_nop 0
	v_pk_mul_f32 v[8:9], v[14:15], v[8:9]
	s_nop 0
	v_pk_mul_f32 v[2:3], v[8:9], v[2:3]
	v_lshl_add_u64 v[8:9], v[94:95], 0, s[78:79]
	v_cvt_pk_bf16_f32 v0, v2, v3
	v_add_co_u32_e64 v2, s[70:71], s1, v8
	s_mov_b32 s1, 0x2d201000
	s_nop 0
	v_addc_co_u32_e64 v3, s[70:71], 0, v9, s[70:71]
	v_add_co_u32_e64 v8, s[70:71], s1, v8
	v_pk_mul_f32 v[14:15], v[4:5], v[4:5]
	s_nop 0
	v_addc_co_u32_e64 v9, s[70:71], 0, v9, s[70:71]
	global_store_dword v[8:9], v0, off offset:-4096
	v_add_f32_e32 v0, v14, v15
	s_mov_b32 s1, 0x11208000
	v_lshl_add_u64 v[94:95], v[94:95], 0, s[76:77]
	s_waitcnt lgkmcnt(0)
	s_nop 1
	v_add_f32_dpp v0, v0, v0 quad_perm:[1,0,3,2] row_mask:0xf bank_mask:0xf
	s_waitcnt lgkmcnt(0)
	s_nop 1
	v_add_f32_dpp v0, v0, v0 quad_perm:[2,3,0,1] row_mask:0xf bank_mask:0xf
	s_waitcnt lgkmcnt(0)
	s_nop 1
	v_add_f32_dpp v0, v0, v0 row_half_mirror row_mask:0xf bank_mask:0xf
	s_waitcnt lgkmcnt(0)
	s_nop 1
	v_add_f32_dpp v0, v0, v0 row_mirror row_mask:0xf bank_mask:0xf
	s_waitcnt lgkmcnt(0)
	v_mov_b32_e32 v13, v0
	s_nop 1
	v_permlane16_swap_b32_e32 v0, v13
	v_add_f32_e32 v0, v0, v13
	s_waitcnt lgkmcnt(0)
	v_mov_b32_e32 v13, v0
	s_nop 1
	v_permlane32_swap_b32_e32 v0, v13
	v_add_f32_e32 v0, v0, v13
	v_fmamk_f32 v0, v0, 0x3c000000, v232
	v_cmp_gt_f32_e64 s[70:71], s4, v0
	v_mul_f32_e32 v13, 0x4b800000, v0
	s_nop 0
	v_cndmask_b32_e64 v0, v0, v13, s[70:71]
	v_rsq_f32_e32 v0, v0
	s_nop 0
	v_mul_f32_e32 v13, 0x45800000, v0
	v_cndmask_b32_e64 v0, v0, v13, s[70:71]
	v_add_co_u32_e64 v14, s[70:71], s1, v10
	v_pk_mul_f32 v[4:5], v[4:5], v[0:1] op_sel_hi:[1,0]
	s_nop 0
	v_addc_co_u32_e64 v15, s[70:71], 0, v11, s[70:71]
	global_load_dword v13, v[14:15], off offset:2048
	v_pk_mul_f32 v[4:5], v[6:7], v[4:5]
	s_mov_b32 s1, 0x1120e000
	s_waitcnt vmcnt(0)
	v_lshlrev_b32_e32 v14, 16, v13
	v_and_b32_e32 v15, 0xffff0000, v13
	v_mul_f32_e32 v13, 0xbfb8aa3b, v14
	v_mul_f32_e32 v0, 0xbfb8aa3b, v15
	v_exp_f32_e32 v13, v13
	v_exp_f32_e32 v0, v0
	v_add_f32_e32 v13, 1.0, v13
	v_add_f32_e32 v0, 1.0, v0
	v_rcp_f32_e32 v16, v13
	v_rcp_f32_e32 v17, v0
	s_nop 0
	v_pk_mul_f32 v[14:15], v[16:17], v[14:15]
	s_nop 0
	v_pk_mul_f32 v[4:5], v[14:15], v[4:5]
	s_nop 0
	v_cvt_pk_bf16_f32 v0, v4, v5
	global_store_dword v[2:3], v0, off offset:2048
	ds_read2_b64 v[2:5], v12 offset0:132 offset1:198
	s_waitcnt lgkmcnt(0)
; __device__ __forceinline__ float sigm(float x) { return __builtin_amdgcn_rcpf(1.0f + __expf(-x)); }
; __device__ __forceinline__ float bflo(unsigned w) { return __uint_as_float(w << 16); }
; __device__ __forceinline__ float bfhi(unsigned w) { return __uint_as_float(w & 0xffff0000u); }
; #define LAS __attribute__((address_space(3)))
; __device__ __forceinline__ unsigned pk2(float lo, float hi) { return pg8::cvt_pk_bf16(lo, hi); }
; __device__ __forceinline__ void ret_out_unit(LAS unsigned char* lds, const bf16* Z, const bf16* RT, const float* subg, bf16* YB, int h, int n, int tid) {
;     ...
;     for (int rr = 0; rr < 16; ++rr) {
;         const int i = wid * 16 + rr;
;         const f32x2 x = *(const LAS f32x2*)(OF + i * 132 + 2 * lane);
;         const float r = rsqrtf(wave_sum(x.x * x.x + x.y * x.y) * (1.f / 128.f) + EPS);
;         const size_t row = (size_t)(n * 128 + i);
;         const unsigned gw = *(const unsigned*)(Z + row * NIN + ZGR + h * 128 + 2 * lane);
;         const float ga = bflo(gw), gb = bfhi(gw);
;         *(unsigned*)(YB + row * 1024 + h * 128 + 2 * lane) = pk2(x.x * r * g2.x * (ga * sigm(ga)), x.y * r * g2.y * (gb * sigm(gb)));
;     }
	v_pk_mul_f32 v[12:13], v[2:3], v[2:3]
	s_nop 0
	v_add_f32_e32 v0, v12, v13
	s_waitcnt lgkmcnt(0)
	s_nop 1
	v_add_f32_dpp v0, v0, v0 quad_perm:[1,0,3,2] row_mask:0xf bank_mask:0xf
	s_waitcnt lgkmcnt(0)
	s_nop 1
	v_add_f32_dpp v0, v0, v0 quad_perm:[2,3,0,1] row_mask:0xf bank_mask:0xf
	s_waitcnt lgkmcnt(0)
	s_nop 1
	v_add_f32_dpp v0, v0, v0 row_half_mirror row_mask:0xf bank_mask:0xf
	s_waitcnt lgkmcnt(0)
	s_nop 1
	v_add_f32_dpp v0, v0, v0 row_mirror row_mask:0xf bank_mask:0xf
	s_waitcnt lgkmcnt(0)
	v_mov_b32_e32 v12, v0
	s_nop 1
	v_permlane16_swap_b32_e32 v0, v12
	v_add_f32_e32 v0, v0, v12
	s_waitcnt lgkmcnt(0)
	v_mov_b32_e32 v12, v0
	s_nop 1
	v_permlane32_swap_b32_e32 v0, v12
	v_add_f32_e32 v0, v0, v12
	v_fmamk_f32 v0, v0, 0x3c000000, v232
	v_cmp_gt_f32_e64 s[70:71], s4, v0
	v_mul_f32_e32 v12, 0x4b800000, v0
	s_nop 0
	v_cndmask_b32_e64 v0, v0, v12, s[70:71]
	v_rsq_f32_e32 v0, v0
	s_nop 0
	v_mul_f32_e32 v12, 0x45800000, v0
	v_cndmask_b32_e64 v0, v0, v12, s[70:71]
	v_add_co_u32_e64 v12, s[70:71], s1, v10
	v_pk_mul_f32 v[2:3], v[2:3], v[0:1] op_sel_hi:[1,0]
	s_nop 0
	v_addc_co_u32_e64 v13, s[70:71], 0, v11, s[70:71]
	global_load_dword v13, v[12:13], off
	v_pk_mul_f32 v[2:3], v[6:7], v[2:3]
	s_mov_b32 s1, 0x11213000
	s_waitcnt vmcnt(0)
	v_lshlrev_b32_e32 v12, 16, v13
	v_and_b32_e32 v13, 0xffff0000, v13
	v_mul_f32_e32 v14, 0xbfb8aa3b, v12
	v_mul_f32_e32 v0, 0xbfb8aa3b, v13
	v_exp_f32_e32 v14, v14
	v_exp_f32_e32 v0, v0
	v_add_f32_e32 v14, 1.0, v14
	v_add_f32_e32 v0, 1.0, v0
	v_rcp_f32_e32 v14, v14
	v_rcp_f32_e32 v15, v0
	s_nop 0
	v_pk_mul_f32 v[12:13], v[14:15], v[12:13]
	s_nop 0
	v_pk_mul_f32 v[2:3], v[12:13], v[2:3]
	s_nop 0
	v_cvt_pk_bf16_f32 v0, v2, v3
	v_pk_mul_f32 v[2:3], v[4:5], v[4:5]
	global_store_dword v[8:9], v0, off
	v_add_f32_e32 v0, v2, v3
	s_waitcnt lgkmcnt(0)
	s_nop 1
	v_add_f32_dpp v0, v0, v0 quad_perm:[1,0,3,2] row_mask:0xf bank_mask:0xf
	s_waitcnt lgkmcnt(0)
	s_nop 1
	v_add_f32_dpp v0, v0, v0 quad_perm:[2,3,0,1] row_mask:0xf bank_mask:0xf
	s_waitcnt lgkmcnt(0)
	s_nop 1
	v_add_f32_dpp v0, v0, v0 row_half_mirror row_mask:0xf bank_mask:0xf
	s_waitcnt lgkmcnt(0)
	s_nop 1
	v_add_f32_dpp v0, v0, v0 row_mirror row_mask:0xf bank_mask:0xf
	s_waitcnt lgkmcnt(0)
	v_mov_b32_e32 v2, v0
	s_nop 1
	v_permlane16_swap_b32_e32 v0, v2
	v_add_f32_e32 v0, v0, v2
	s_waitcnt lgkmcnt(0)
	v_mov_b32_e32 v2, v0
	s_nop 1
	v_permlane32_swap_b32_e32 v0, v2
	v_add_f32_e32 v0, v0, v2
	v_fmamk_f32 v0, v0, 0x3c000000, v232
	v_cmp_gt_f32_e64 s[70:71], s4, v0
	v_mul_f32_e32 v2, 0x4b800000, v0
	s_nop 0
	v_cndmask_b32_e64 v0, v0, v2, s[70:71]
	v_rsq_f32_e32 v0, v0
	s_nop 0
	v_mul_f32_e32 v2, 0x45800000, v0
	v_cndmask_b32_e64 v0, v0, v2, s[70:71]
	v_add_co_u32_e64 v2, s[70:71], s1, v10
	v_pk_mul_f32 v[4:5], v[4:5], v[0:1] op_sel_hi:[1,0]
	s_nop 0
	v_addc_co_u32_e64 v3, s[70:71], 0, v11, s[70:71]
	global_load_dword v3, v[2:3], off offset:2048
	v_pk_mul_f32 v[4:5], v[6:7], v[4:5]
	s_mov_b64 s[70:71], 0x16000
	v_lshl_add_u64 v[92:93], v[92:93], 0, s[70:71]
	s_waitcnt vmcnt(0)
	v_lshlrev_b32_e32 v2, 16, v3
	v_and_b32_e32 v3, 0xffff0000, v3
	v_mul_f32_e32 v10, 0xbfb8aa3b, v2
	v_mul_f32_e32 v0, 0xbfb8aa3b, v3
	v_exp_f32_e32 v10, v10
	v_exp_f32_e32 v0, v0
	v_add_f32_e32 v10, 1.0, v10
	v_add_f32_e32 v0, 1.0, v0
	v_rcp_f32_e32 v10, v10
	v_rcp_f32_e32 v11, v0
	s_nop 0
	v_pk_mul_f32 v[2:3], v[10:11], v[2:3]
	s_nop 0
	v_pk_mul_f32 v[2:3], v[2:3], v[4:5]
	s_nop 0
	v_cvt_pk_bf16_f32 v0, v2, v3
	global_store_dword v[8:9], v0, off offset:2048
	s_cbranch_scc1 .LBB0_15
	s_add_i32 s0, s0, s2
	s_add_i32 s3, s3, s2
	s_cmpk_gt_i32 s0, 0x3ff
	s_barrier
	s_cbranch_scc0 .LBB0_14
